# both MLA tile loops software-pipelined with LDS-DMA pieces interleaved (saddr form); diff-attention DMA pieces spread over QK and PV MFMAs
# speedup vs baseline: 1.0291x; 1.0185x over previous
; template <bool DIFF, bool NOMAX>
; DI void unit(LAS unsigned char* lds, const Tensors& Tn, int b, int hd, int qb) {
;     ...
;                 for (int ks = 0; ks < NKS; ++ks) {
;                     sc = mfma32(kf[ks % DK], qf[ks], sc);
;                     if (ks + DK < NKS) kf[ks % DK] = LDK(hf, ks + DK);
;                 }
; #pragma unroll
;                 for (int ks = 0; ks < NKS; ++ks) { SGB(0x8, 1); if (ks + DK < NKS) SGB(0x100, 1); }
;                 __builtin_amdgcn_sched_barrier(0);
; #pragma unroll
;                 for (int i = 0; i < DV; ++i) LDV(i, hf);
;                 if (DIFF && !offd) {
;                     const float qk = (float)(q0 + r - 64 * j - 4 * h - 32 * hf);
;                     float tq[4] = {qk, qk - 8.f, qk - 16.f, qk - 24.f};
; #pragma unroll
;                     for (int g = 0; g < 4; ++g) asm volatile("" : "+v"(tq[g]));
; #pragma unroll
;                     for (int e = 0; e < 16; ++e) sc[e] = __builtin_fmaf(-sl2, __builtin_fabsf(tq[e >> 2] - (float)(e & 3)), sc[e]);
;                 }
;                 float mx = sc[0];
;                 if (!NOMAX) {
; #pragma unroll
;                 for (int e = 1; e < 16; ++e) mx = __builtin_fmaxf(mx, sc[e]);
;                 { auto rr = __builtin_amdgcn_permlane32_swap(__builtin_bit_cast(unsigned, mx), __builtin_bit_cast(unsigned, mx), false, false);
;                   mx = __builtin_fmaxf(__builtin_bit_cast(float, rr[0]), __builtin_bit_cast(float, rr[1])); }
;                 }
;                 const bool first = (j == jst) && (hf == 0);
;                 if (!NOMAX && (first || __any(mx > 8.0f))) {
;                     const float mn = first ? mx : __builtin_fmaxf(mx, 0.f), al = first ? 1.0f : fast_exp2(-mn);
; #pragma unroll
;                     for (int dt = 0; dt < NDT; ++dt) o[dt] = o[dt] * al;
;                     lrow *= al; mrow += mn;
; #pragma unroll
;                     for (int e = 0; e < 16; ++e) sc[e] -= mn;
;                 }
;                 f32x2_t ps2 = {0.f, 0.f};
; #pragma unroll
;                 for (int e = 0; e < 16; e += 2) { sc[e] = fast_exp2(sc[e]); sc[e + 1] = fast_exp2(sc[e + 1]); ps2 += (f32x2_t){sc[e], sc[e + 1]}; }
;                 lrow += ps2.x + ps2.y;
;                 bf16x8 pb[2]; pb[0] = pack8(sc, 0); pb[1] = pack8(sc, 1);
; #pragma unroll
;                 for (int i = 0; i < NPV; ++i) {
.Ldf_skip0:
	ds_read_b128 v[192:195], v250 offset:128
	v_mfma_f32_32x32x16_bf16 v[132:147], v[188:191], v[152:155], v[132:147]
	ds_read_b128 v[188:191], v250 offset:160
	v_mfma_f32_32x32x16_bf16 v[132:147], v[184:187], v[156:159], v[132:147]
	s_and_b64 vcc, exec, s[74:75]
	s_cbranch_vccnz .Ldf_skip1
	s_andn2_b64 vcc, exec, s[56:57]
	s_cbranch_vccnz .Ldf_skip1
	s_add_i32 m0, s98, s26
	s_nop 0
	global_load_lds_dwordx4 v206, s[72:73]
.Ldf_skip1:
	ds_read_b128 v[184:187], v250 offset:192
	v_mfma_f32_32x32x16_bf16 v[132:147], v[180:183], v[160:163], v[132:147]
	ds_read_b128 v[180:183], v250 offset:224
	s_waitcnt lgkmcnt(0)
	v_mfma_f32_32x32x16_bf16 v[132:147], v[192:195], v[164:167], v[132:147]
	s_and_b64 vcc, exec, s[74:75]
	s_cbranch_vccnz .Ldf_skip2
	s_andn2_b64 vcc, exec, s[58:59]
	s_cbranch_vccnz .Ldf_skip2
	s_add_i32 m0, s98, s27
	s_nop 0
	global_load_lds_dwordx4 v208, s[72:73]
.Ldf_skip2:
	v_mfma_f32_32x32x16_bf16 v[132:147], v[188:191], v[168:171], v[132:147]
	v_mfma_f32_32x32x16_bf16 v[132:147], v[184:187], v[172:175], v[132:147]
	s_and_b64 vcc, exec, s[74:75]
	s_cbranch_vccnz .Ldf_skip3
	s_andn2_b64 vcc, exec, s[60:61]
	s_cbranch_vccnz .Ldf_skip3
	s_add_i32 m0, s98, s51
	s_nop 0
	global_load_lds_dwordx4 v210, s[72:73]
.Ldf_skip3:
	v_add_u32_e32 v184, s83, v245
	v_add3_u32 v249, v184, v246, s84
	v_mfma_f32_32x32x16_bf16 v[132:147], v[180:183], v[176:179], v[132:147]
	ds_read_b64_tr_b16 v[184:185], v249 offset:0
	ds_read_b64_tr_b16 v[186:187], v249 offset:4608
	ds_read_b64_tr_b16 v[180:181], v249 offset:9216
	v_cndmask_b32_e64 v182, 0, 1, s[76:77]
	v_cmp_ne_u32_e64 s[4:5], 1, v182
	ds_read_b64_tr_b16 v[182:183], v249 offset:13824
	s_andn2_b64 vcc, exec, s[76:77]
	s_cbranch_vccnz .LBB0_802
	v_add_u32_e32 v188, 32, v248
	v_cvt_f32_i32_e32 v188, v188
	v_mov_b32_e32 v201, v200
	v_add_f32_e32 v190, 0xc1000000, v188
	v_add_f32_e32 v192, 0xc1800000, v188
	v_add_f32_e32 v194, 0xc1c00000, v188
	s_nop 0
	v_add_f32_e32 v189, -1.0, v188
	v_add_f32_e32 v191, -1.0, v190
	v_add_f32_e32 v193, -1.0, v192
	v_add_f32_e32 v195, -1.0, v194
	v_pk_add_f32 v[222:223], v[188:189], s[54:55] op_sel_hi:[0,1]
	v_pk_add_f32 v[224:225], v[190:191], s[54:55] op_sel_hi:[0,1]
	v_pk_add_f32 v[226:227], v[192:193], s[54:55] op_sel_hi:[0,1]
	v_pk_add_f32 v[228:229], v[194:195], s[54:55] op_sel_hi:[0,1]
	v_and_b32_e32 v229, 0x7fffffff, v229
	v_and_b32_e32 v228, 0x7fffffff, v228
	v_and_b32_e32 v227, 0x7fffffff, v227
	v_and_b32_e32 v226, 0x7fffffff, v226
	v_and_b32_e32 v225, 0x7fffffff, v225
	v_and_b32_e32 v224, 0x7fffffff, v224
	v_and_b32_e32 v223, 0x7fffffff, v223
	v_and_b32_e32 v222, 0x7fffffff, v222
	v_and_b32_e32 v194, 0x7fffffff, v194
	v_and_b32_e32 v195, 0x7fffffff, v195
	v_and_b32_e32 v192, 0x7fffffff, v192
	v_and_b32_e32 v193, 0x7fffffff, v193
	v_and_b32_e32 v190, 0x7fffffff, v190
	v_and_b32_e32 v191, 0x7fffffff, v191
	v_and_b32_e32 v188, 0x7fffffff, v188
	v_and_b32_e32 v189, 0x7fffffff, v189
	v_pk_fma_f32 v[134:135], v[200:201], v[222:223], v[134:135]
	v_pk_fma_f32 v[138:139], v[200:201], v[224:225], v[138:139]
	v_pk_fma_f32 v[142:143], v[200:201], v[226:227], v[142:143]
	v_pk_fma_f32 v[146:147], v[200:201], v[228:229], v[146:147]
	v_pk_fma_f32 v[132:133], v[202:203], v[188:189], v[132:133]
	v_pk_fma_f32 v[136:137], v[200:201], v[190:191], v[136:137]
	v_pk_fma_f32 v[140:141], v[200:201], v[192:193], v[140:141]
	v_pk_fma_f32 v[144:145], v[200:201], v[194:195], v[144:145]
.LBB0_802:
	s_waitcnt lgkmcnt(2)
	s_nop 7
	v_exp_f32_e32 v236, v132
	v_exp_f32_e32 v237, v133
	v_exp_f32_e32 v234, v134
	v_exp_f32_e32 v235, v135
	v_exp_f32_e32 v232, v136
	v_exp_f32_e32 v233, v137
	v_exp_f32_e32 v230, v138
	v_exp_f32_e32 v231, v139
	v_exp_f32_e32 v228, v140
	v_exp_f32_e32 v229, v141
	ds_read_b64_tr_b16 v[140:141], v249 offset:64
	v_exp_f32_e32 v226, v142
	v_exp_f32_e32 v227, v143
	ds_read_b64_tr_b16 v[142:143], v249 offset:4672
	s_waitcnt lgkmcnt(2)
	v_exp_f32_e32 v224, v144
	v_exp_f32_e32 v225, v145
	ds_read_b64_tr_b16 v[144:145], v249 offset:9280
	v_exp_f32_e32 v222, v146
	v_exp_f32_e32 v223, v147
	v_cvt_pk_bf16_f32 v132, v236, v237
	v_cvt_pk_bf16_f32 v133, v234, v235
	v_cvt_pk_bf16_f32 v134, v232, v233
	v_cvt_pk_bf16_f32 v135, v230, v231
	ds_read_b64_tr_b16 v[146:147], v249 offset:13888
	s_waitcnt lgkmcnt(2)
	v_cvt_pk_bf16_f32 v136, v228, v229
	v_cvt_pk_bf16_f32 v137, v226, v227
	v_mfma_f32_32x32x16_bf16 v[98:113], v[140:143], v[132:135], v[98:113]
	ds_read_b64_tr_b16 v[140:141], v249 offset:128
	ds_read_b64_tr_b16 v[142:143], v249 offset:4736
	v_cvt_pk_bf16_f32 v138, v224, v225
	v_cvt_pk_bf16_f32 v139, v222, v223
	s_waitcnt lgkmcnt(2)
	s_nop 1
	v_mfma_f32_32x32x16_bf16 v[98:113], v[144:147], v[136:139], v[98:113]
	s_and_b64 vcc, exec, s[74:75]
	s_cbranch_vccnz .Ldf_skip4
	s_andn2_b64 vcc, exec, s[62:63]
	s_cbranch_vccnz .Ldf_skip4
	s_add_i32 m0, s98, s46
	s_nop 0
	global_load_lds_dwordx4 v212, s[72:73]
; DI f32x16 mfma32(bf16x8 a, bf16x8 b, f32x16 c) { return __builtin_amdgcn_mfma_f32_32x32x16_bf16(a, b, c, 0, 0, 0); }
; #define SGB(mask, n) __builtin_amdgcn_sched_group_barrier(mask, n, 0)
; #define LDV(i_, hf_) do { VTR(vlo[(i_) % DV], (16 * (2 * (hf_) + ((i_) & 1))) * VSTR + 64 * ((i_) >> 1)); VTR(vhi[(i_) % DV], (16 * (2 * (hf_) + ((i_) & 1)) + 8) * VSTR + 64 * ((i_) >> 1)); } while (0)
; #define VWAIT(n_, a_, b_) asm volatile("s_waitcnt lgkmcnt(%c2)" : "+v"(a_), "+v"(b_) : "i"(n_) : "memory")
; template <bool DIFF, bool NOMAX>
; DI void unit(LAS unsigned char* lds, const Tensors& Tn, int b, int hd, int qb) {
;     ...
;                 for (int i = 0; i < NPV; ++i) {
;                     VWAIT(2 * ((NPV - 1 - i) < (DV - 1) ? (NPV - 1 - i) : (DV - 1)), vlo[i % DV], vhi[i % DV]);
;                     const bf16x8 vf = __builtin_shufflevector(vlo[i % DV], vhi[i % DV], 0, 1, 2, 3, 4, 5, 6, 7);
;                     o[i >> 1] = mfma32(vf, pb[i & 1], o[i >> 1]);
;                     if (i + DV < NPV) LDV(i + DV, hf);
;                 }
;                 __builtin_amdgcn_sched_barrier(0);
;                 if (hf == 0) {
; #pragma unroll
;                     for (int i = 0; i < DK; ++i) kf[i] = LDK(1, i);
;                     SGB(0x100, DK);
;                 }
.Ldf_skip4:
	ds_read_b64_tr_b16 v[144:145], v249 offset:9344
	ds_read_b64_tr_b16 v[146:147], v249 offset:13952
	s_waitcnt lgkmcnt(2)
	s_nop 0
	v_mfma_f32_32x32x16_bf16 v[82:97], v[140:143], v[132:135], v[82:97]
	ds_read_b64_tr_b16 v[140:141], v249 offset:192
	ds_read_b64_tr_b16 v[142:143], v249 offset:4800
	s_waitcnt lgkmcnt(2)
	s_nop 0
	v_mfma_f32_32x32x16_bf16 v[82:97], v[144:147], v[136:139], v[82:97]
	ds_read_b64_tr_b16 v[144:145], v249 offset:9408
	ds_read_b64_tr_b16 v[146:147], v249 offset:14016
	s_waitcnt lgkmcnt(2)
	s_nop 0
	v_mfma_f32_32x32x16_bf16 v[66:81], v[140:143], v[132:135], v[66:81]
	s_and_b64 vcc, exec, s[74:75]
	s_cbranch_vccnz .Ldf_skip5
	s_andn2_b64 vcc, exec, s[64:65]
	s_cbranch_vccnz .Ldf_skip5
	s_add_i32 m0, s98, s47
	s_nop 0
	global_load_lds_dwordx4 v214, s[72:73]
.Ldf_skip5:
	ds_read_b64_tr_b16 v[140:141], v249 offset:256
	ds_read_b64_tr_b16 v[142:143], v249 offset:4864
	s_waitcnt lgkmcnt(2)
	s_nop 0
	v_mfma_f32_32x32x16_bf16 v[66:81], v[144:147], v[136:139], v[66:81]
	ds_read_b64_tr_b16 v[144:145], v249 offset:9472
	ds_read_b64_tr_b16 v[146:147], v249 offset:14080
	s_waitcnt lgkmcnt(2)
	s_nop 0
	v_mfma_f32_32x32x16_bf16 v[50:65], v[140:143], v[132:135], v[50:65]
	ds_read_b64_tr_b16 v[140:141], v249 offset:320
	ds_read_b64_tr_b16 v[142:143], v249 offset:4928
	s_waitcnt lgkmcnt(2)
	s_nop 0
	v_mfma_f32_32x32x16_bf16 v[50:65], v[144:147], v[136:139], v[50:65]
	s_and_b64 vcc, exec, s[74:75]
	s_cbranch_vccnz .Ldf_skip6
	s_andn2_b64 vcc, exec, s[66:67]
	s_cbranch_vccnz .Ldf_skip6
	s_add_i32 m0, s98, s79
	s_nop 0
	global_load_lds_dwordx4 v216, s[72:73]
.Ldf_skip6:
	ds_read_b64_tr_b16 v[144:145], v249 offset:9536
	ds_read_b64_tr_b16 v[146:147], v249 offset:14144
	s_waitcnt lgkmcnt(2)
	s_nop 0
	v_mfma_f32_32x32x16_bf16 v[34:49], v[140:143], v[132:135], v[34:49]
	ds_read_b64_tr_b16 v[140:141], v249 offset:384
	ds_read_b64_tr_b16 v[142:143], v249 offset:4992
	s_waitcnt lgkmcnt(2)
	s_nop 0
	v_mfma_f32_32x32x16_bf16 v[34:49], v[144:147], v[136:139], v[34:49]
	ds_read_b64_tr_b16 v[144:145], v249 offset:9600
	ds_read_b64_tr_b16 v[146:147], v249 offset:14208
	s_waitcnt lgkmcnt(2)
	s_nop 0
	v_mfma_f32_32x32x16_bf16 v[18:33], v[140:143], v[132:135], v[18:33]
	s_and_b64 vcc, exec, s[74:75]
	s_cbranch_vccnz .Ldf_skip7
	s_andn2_b64 vcc, exec, s[68:69]
	s_cbranch_vccnz .Ldf_skip7
	s_add_i32 m0, s98, s80
	s_nop 0
	global_load_lds_dwordx4 v218, s[72:73]
.Ldf_skip7:
	ds_read_b64_tr_b16 v[140:141], v249 offset:448
	ds_read_b64_tr_b16 v[142:143], v249 offset:5056
	s_waitcnt lgkmcnt(2)
	s_nop 0
	v_mfma_f32_32x32x16_bf16 v[18:33], v[144:147], v[136:139], v[18:33]
	ds_read_b64_tr_b16 v[144:145], v249 offset:9664
	ds_read_b64_tr_b16 v[146:147], v249 offset:14272
	s_waitcnt lgkmcnt(2)
	s_nop 0
	s_waitcnt lgkmcnt(0)
	v_mfma_f32_32x32x16_bf16 v[114:129], v[184:187], v[132:135], v[114:129]
	v_mfma_f32_32x32x16_bf16 v[2:17], v[140:143], v[132:135], v[2:17]
	s_and_b64 vcc, exec, s[74:75]
	s_cbranch_vccnz .Ldf_skip8
	s_andn2_b64 vcc, exec, s[70:71]
	s_cbranch_vccnz .Ldf_skip8
	s_add_i32 m0, s98, s81
	s_nop 0
	global_load_lds_dwordx4 v220, s[72:73]
.Ldf_skip8:
	v_mfma_f32_32x32x16_bf16 v[114:129], v[180:183], v[136:139], v[114:129]
	v_mfma_f32_32x32x16_bf16 v[2:17], v[144:147], v[136:139], v[2:17]
	ds_read_b128 v[192:195], v250 offset:16896
	ds_read_b128 v[188:191], v250 offset:16928
	ds_read_b128 v[184:187], v250 offset:16960
	ds_read_b128 v[180:183], v250 offset:16992
	s_and_b64 vcc, exec, s[4:5]
	s_mov_b64 s[76:77], -1
	s_cbranch_vccnz .LBB0_804
	s_mov_b64 s[76:77], 0

; DI float fast_exp2(float x) { return __builtin_amdgcn_exp2f(x); }
; template <bool DIFF, bool NOMAX>
; DI void unit(LAS unsigned char* lds, const Tensors& Tn, int b, int hd, int qb) {
;     ...
; #pragma unroll
;                 for (int ks = 0; ks < NKS; ++ks) {
;                     sc = mfma32(kf[ks % DK], qf[ks], sc);
;                     if (ks + DK < NKS) kf[ks % DK] = LDK(hf, ks + DK);
;                 }
; #pragma unroll
;                 for (int ks = 0; ks < NKS; ++ks) { SGB(0x8, 1); if (ks + DK < NKS) SGB(0x100, 1); }
;                 __builtin_amdgcn_sched_barrier(0);
; #pragma unroll
;                 for (int i = 0; i < DV; ++i) LDV(i, hf);
;                 if (DIFF && !offd) {
;                     const float qk = (float)(q0 + r - 64 * j - 4 * h - 32 * hf);
;                     float tq[4] = {qk, qk - 8.f, qk - 16.f, qk - 24.f};
; #pragma unroll
;                     for (int g = 0; g < 4; ++g) asm volatile("" : "+v"(tq[g]));
; #pragma unroll
;                     for (int e = 0; e < 16; ++e) sc[e] = __builtin_fmaf(-sl2, __builtin_fabsf(tq[e >> 2] - (float)(e & 3)), sc[e]);
;                 }
;                 float mx = sc[0];
;                 if (!NOMAX) {
; #pragma unroll
;                 for (int e = 1; e < 16; ++e) mx = __builtin_fmaxf(mx, sc[e]);
;                 { auto rr = __builtin_amdgcn_permlane32_swap(__builtin_bit_cast(unsigned, mx), __builtin_bit_cast(unsigned, mx), false, false);
;                   mx = __builtin_fmaxf(__builtin_bit_cast(float, rr[0]), __builtin_bit_cast(float, rr[1])); }
;                 }
;                 const bool first = (j == jst) && (hf == 0);
;                 if (!NOMAX && (first || __any(mx > 8.0f))) {
;                     const float mn = first ? mx : __builtin_fmaxf(mx, 0.f), al = first ? 1.0f : fast_exp2(-mn);
; #pragma unroll
;                     for (int dt = 0; dt < NDT; ++dt) o[dt] = o[dt] * al;
;                     lrow *= al; mrow += mn;
; #pragma unroll
;                     for (int e = 0; e < 16; ++e) sc[e] -= mn;
;                 }
;                 f32x2_t ps2 = {0.f, 0.f};
; #pragma unroll
;                 for (int e = 0; e < 16; e += 2) { sc[e] = fast_exp2(sc[e]); sc[e + 1] = fast_exp2(sc[e + 1]); ps2 += (f32x2_t){sc[e], sc[e + 1]}; }
;                 lrow += ps2.x + ps2.y;
;                 bf16x8 pb[2]; pb[0] = pack8(sc, 0); pb[1] = pack8(sc, 1);
.LBB0_1389:
	s_mul_i32 s80, s51, 0xb400
	s_add_i32 s80, s80, 0
	v_add3_u32 v0, s80, v170, v144
	s_add_i32 s99, s84, 2
	s_cmp_lt_u32 s99, s29
	s_cselect_b32 s99, 1, 0
	s_cmp_gt_i32 s51, 0
	s_cselect_b32 s98, -1, 2
	s_add_i32 s98, s98, s51
	s_mul_i32 s98, s98, 0xb400
	v_mov_b32_e32 v196, 0
	ds_read_b128 v[2:5], v0
	ds_read_b128 v[6:9], v0 offset:32
	ds_read_b128 v[10:13], v0 offset:64
	ds_read_b128 v[174:177], v0 offset:96
	ds_read_b128 v[178:181], v0 offset:128
	ds_read_b128 v[182:185], v0 offset:160
	v_add_u32_e32 v14, s80, v145
	v_add3_u32 v173, v14, v171, s1
	s_waitcnt lgkmcnt(5)
	v_mfma_f32_32x32x16_bf16 v[80:95], v[2:5], v[96:99], 0
	ds_read_b128 v[2:5], v0 offset:192
	s_waitcnt lgkmcnt(5)
	v_mfma_f32_32x32x16_bf16 v[80:95], v[6:9], v[100:103], v[80:95]
	ds_read_b128 v[6:9], v0 offset:224
	s_waitcnt lgkmcnt(5)
	v_mfma_f32_32x32x16_bf16 v[80:95], v[10:13], v[104:107], v[80:95]
	ds_read_b128 v[10:13], v0 offset:256
	s_waitcnt lgkmcnt(5)
	v_mfma_f32_32x32x16_bf16 v[80:95], v[174:177], v[108:111], v[80:95]
	ds_read_b128 v[174:177], v0 offset:288
	s_cmp_lg_u32 s99, 0
	s_cbranch_scc0 .Lpc_skip0_i1
	s_and_b64 vcc, exec, s[4:5]
	s_cbranch_vccnz .Lpc_skip0_i1
	v_cndmask_b32_e64 v244, v158, v146, s[14:15]
	s_add_i32 m0, s98, s41
	s_nop 0
	global_load_lds_dwordx4 v244, s[36:37]
.Lpc_skip0_i1:
	s_waitcnt lgkmcnt(5)
	v_mfma_f32_32x32x16_bf16 v[80:95], v[178:181], v[112:115], v[80:95]
	ds_read_b128 v[178:181], v0 offset:320
	s_waitcnt lgkmcnt(5)
	v_mfma_f32_32x32x16_bf16 v[80:95], v[182:185], v[116:119], v[80:95]
	ds_read_b128 v[182:185], v0 offset:352
	s_waitcnt lgkmcnt(5)
	v_mfma_f32_32x32x16_bf16 v[80:95], v[2:5], v[120:123], v[80:95]
	ds_read_b128 v[2:5], v0 offset:12800
	s_waitcnt lgkmcnt(5)
	v_mfma_f32_32x32x16_bf16 v[80:95], v[6:9], v[124:127], v[80:95]
	ds_read_b128 v[6:9], v0 offset:12832
	s_waitcnt lgkmcnt(5)
	v_mfma_f32_32x32x16_bf16 v[80:95], v[10:13], v[128:131], v[80:95]
	ds_read_b128 v[10:13], v0 offset:12864
	s_waitcnt lgkmcnt(5)
	v_mfma_f32_32x32x16_bf16 v[80:95], v[174:177], v[132:135], v[80:95]
	ds_read_b128 v[174:177], v0 offset:12896
	s_waitcnt lgkmcnt(5)
	v_mfma_f32_32x32x16_bf16 v[80:95], v[178:181], v[136:139], v[80:95]
	ds_read_b128 v[178:181], v0 offset:12928
	s_cmp_lg_u32 s99, 0
	s_cbranch_scc0 .Lpc_skip1_i1
	s_and_b64 vcc, exec, s[6:7]
	s_cbranch_vccnz .Lpc_skip1_i1
	v_cndmask_b32_e64 v244, v160, v148, s[16:17]
	s_add_i32 m0, s98, s56
	s_nop 0
	global_load_lds_dwordx4 v244, s[36:37]
.Lpc_skip1_i1:
	s_waitcnt lgkmcnt(5)
	v_mfma_f32_32x32x16_bf16 v[80:95], v[182:185], v[140:143], v[80:95]
	ds_read_b128 v[182:185], v0 offset:12960
	s_waitcnt lgkmcnt(5)
	v_mfma_f32_32x32x16_bf16 v[226:241], v[2:5], v[96:99], 0
	ds_read_b128 v[2:5], v0 offset:12992
	s_waitcnt lgkmcnt(5)
	v_mfma_f32_32x32x16_bf16 v[226:241], v[6:9], v[100:103], v[226:241]
	ds_read_b128 v[6:9], v0 offset:13024
	s_waitcnt lgkmcnt(5)
	v_mfma_f32_32x32x16_bf16 v[226:241], v[10:13], v[104:107], v[226:241]
	ds_read_b128 v[10:13], v0 offset:13056
	s_waitcnt lgkmcnt(5)
	v_mfma_f32_32x32x16_bf16 v[226:241], v[174:177], v[108:111], v[226:241]
	ds_read_b128 v[174:177], v0 offset:13088
	v_exp_f32_e32 v80, v80
	v_exp_f32_e32 v81, v81
	v_add_f32_e32 v172, v172, v80
	v_add_f32_e32 v196, v196, v81
	s_waitcnt lgkmcnt(5)
	v_mfma_f32_32x32x16_bf16 v[226:241], v[178:181], v[112:115], v[226:241]
	ds_read_b128 v[178:181], v0 offset:13120
	v_cvt_pk_bf16_f32 v80, v80, v81
	v_exp_f32_e32 v82, v82
	v_exp_f32_e32 v83, v83
	v_add_f32_e32 v172, v172, v82
	s_waitcnt lgkmcnt(5)
	v_mfma_f32_32x32x16_bf16 v[226:241], v[182:185], v[116:119], v[226:241]
	ds_read_b128 v[182:185], v0 offset:13152
	v_add_f32_e32 v196, v196, v83
	v_cvt_pk_bf16_f32 v81, v82, v83
	v_exp_f32_e32 v84, v84
	v_exp_f32_e32 v85, v85
	s_cmp_lg_u32 s99, 0
	s_cbranch_scc0 .Lpc_skip2_i1
	s_and_b64 vcc, exec, s[8:9]
	s_cbranch_vccnz .Lpc_skip2_i1
	v_cndmask_b32_e64 v244, v162, v150, s[18:19]
	s_add_i32 m0, s98, s57
	s_nop 0
	global_load_lds_dwordx4 v244, s[36:37]
; DI float fast_exp2(float x) { return __builtin_amdgcn_exp2f(x); }
; DI f32x16 mfma32(bf16x8 a, bf16x8 b, f32x16 c) { return __builtin_amdgcn_mfma_f32_32x32x16_bf16(a, b, c, 0, 0, 0); }
; #define LDV(i_, hf_) do { VTR(vlo[(i_) % DV], (16 * (2 * (hf_) + ((i_) & 1))) * VSTR + 64 * ((i_) >> 1)); VTR(vhi[(i_) % DV], (16 * (2 * (hf_) + ((i_) & 1)) + 8) * VSTR + 64 * ((i_) >> 1)); } while (0)
; #define VWAIT(n_, a_, b_) asm volatile("s_waitcnt lgkmcnt(%c2)" : "+v"(a_), "+v"(b_) : "i"(n_) : "memory")
; template <bool DIFF, bool NOMAX>
; DI void unit(LAS unsigned char* lds, const Tensors& Tn, int b, int hd, int qb) {
;     ...
;                 f32x2_t ps2 = {0.f, 0.f};
; #pragma unroll
;                 for (int e = 0; e < 16; e += 2) { sc[e] = fast_exp2(sc[e]); sc[e + 1] = fast_exp2(sc[e + 1]); ps2 += (f32x2_t){sc[e], sc[e + 1]}; }
;                 lrow += ps2.x + ps2.y;
;                 bf16x8 pb[2]; pb[0] = pack8(sc, 0); pb[1] = pack8(sc, 1);
; #pragma unroll
;                 for (int i = 0; i < NPV; ++i) {
;                     VWAIT(2 * ((NPV - 1 - i) < (DV - 1) ? (NPV - 1 - i) : (DV - 1)), vlo[i % DV], vhi[i % DV]);
;                     const bf16x8 vf = __builtin_shufflevector(vlo[i % DV], vhi[i % DV], 0, 1, 2, 3, 4, 5, 6, 7);
;                     o[i >> 1] = mfma32(vf, pb[i & 1], o[i >> 1]);
;                     if (i + DV < NPV) LDV(i + DV, hf);
;                 }
.Lpc_skip2_i1:
	s_waitcnt lgkmcnt(5)
	v_mfma_f32_32x32x16_bf16 v[226:241], v[2:5], v[120:123], v[226:241]
	ds_read_b64_tr_b16 v[2:3], v173 offset:0
	ds_read_b64_tr_b16 v[4:5], v173 offset:2560
	v_add_f32_e32 v172, v172, v84
	v_add_f32_e32 v196, v196, v85
	v_cvt_pk_bf16_f32 v82, v84, v85
	v_exp_f32_e32 v86, v86
	v_exp_f32_e32 v87, v87
	s_waitcnt lgkmcnt(6)
	v_mfma_f32_32x32x16_bf16 v[226:241], v[6:9], v[124:127], v[226:241]
	ds_read_b64_tr_b16 v[6:7], v173 offset:64
	ds_read_b64_tr_b16 v[8:9], v173 offset:2624
	v_add_f32_e32 v172, v172, v86
	v_add_f32_e32 v196, v196, v87
	v_cvt_pk_bf16_f32 v83, v86, v87
	v_exp_f32_e32 v88, v88
	v_exp_f32_e32 v89, v89
	s_waitcnt lgkmcnt(7)
	v_mfma_f32_32x32x16_bf16 v[226:241], v[10:13], v[128:131], v[226:241]
	ds_read_b64_tr_b16 v[10:11], v173 offset:128
	ds_read_b64_tr_b16 v[12:13], v173 offset:2688
	v_add_f32_e32 v172, v172, v88
	v_add_f32_e32 v196, v196, v89
	v_cvt_pk_bf16_f32 v84, v88, v89
	v_exp_f32_e32 v90, v90
	v_exp_f32_e32 v91, v91
	s_waitcnt lgkmcnt(8)
	v_mfma_f32_32x32x16_bf16 v[226:241], v[174:177], v[132:135], v[226:241]
	ds_read_b64_tr_b16 v[174:175], v173 offset:192
	ds_read_b64_tr_b16 v[176:177], v173 offset:2752
	v_add_f32_e32 v172, v172, v90
	v_add_f32_e32 v196, v196, v91
	v_cvt_pk_bf16_f32 v85, v90, v91
	v_exp_f32_e32 v92, v92
	v_exp_f32_e32 v93, v93
	s_waitcnt lgkmcnt(9)
	v_mfma_f32_32x32x16_bf16 v[226:241], v[178:181], v[136:139], v[226:241]
	ds_read_b64_tr_b16 v[178:179], v173 offset:5120
	ds_read_b64_tr_b16 v[180:181], v173 offset:7680
	v_add_f32_e32 v172, v172, v92
	v_add_f32_e32 v196, v196, v93
	v_cvt_pk_bf16_f32 v86, v92, v93
	v_exp_f32_e32 v94, v94
	s_waitcnt lgkmcnt(10)
	v_mfma_f32_32x32x16_bf16 v[226:241], v[182:185], v[140:143], v[226:241]
	ds_read_b64_tr_b16 v[182:183], v173 offset:5184
	ds_read_b64_tr_b16 v[184:185], v173 offset:7744
	v_exp_f32_e32 v95, v95
	v_add_f32_e32 v172, v172, v94
	v_add_f32_e32 v196, v196, v95
	v_cvt_pk_bf16_f32 v87, v94, v95
	s_waitcnt lgkmcnt(10)
	v_mfma_f32_32x32x16_bf16 v[64:79], v[2:5], v[80:83], v[64:79]
	ds_read_b64_tr_b16 v[2:3], v173 offset:5248
	ds_read_b64_tr_b16 v[4:5], v173 offset:7808
	s_cmp_lg_u32 s99, 0
	s_cbranch_scc0 .Lpc_skip3_i1
	s_and_b64 vcc, exec, s[10:11]
	s_cbranch_vccnz .Lpc_skip3_i1
	v_cndmask_b32_e64 v244, v164, v152, s[20:21]
	s_add_i32 m0, s98, s82
	s_nop 0
	global_load_lds_dwordx4 v244, s[36:37]
.Lpc_skip3_i1:
	s_waitcnt lgkmcnt(10)
	v_mfma_f32_32x32x16_bf16 v[48:63], v[6:9], v[80:83], v[48:63]
	ds_read_b64_tr_b16 v[6:7], v173 offset:5312
	ds_read_b64_tr_b16 v[8:9], v173 offset:7872
	s_waitcnt lgkmcnt(10)
	v_mfma_f32_32x32x16_bf16 v[32:47], v[10:13], v[80:83], v[32:47]
	ds_read_b64_tr_b16 v[10:11], v173 offset:10240
	ds_read_b64_tr_b16 v[12:13], v173 offset:12800
	v_exp_f32_e32 v226, v226
	v_exp_f32_e32 v227, v227
	v_add_f32_e32 v172, v172, v226
	v_add_f32_e32 v196, v196, v227
	s_waitcnt lgkmcnt(10)
	v_mfma_f32_32x32x16_bf16 v[16:31], v[174:177], v[80:83], v[16:31]
	ds_read_b64_tr_b16 v[174:175], v173 offset:10304
	ds_read_b64_tr_b16 v[176:177], v173 offset:12864
	v_cvt_pk_bf16_f32 v226, v226, v227
	v_exp_f32_e32 v228, v228
	v_exp_f32_e32 v229, v229
	v_add_f32_e32 v172, v172, v228
	s_waitcnt lgkmcnt(10)
	v_mfma_f32_32x32x16_bf16 v[64:79], v[178:181], v[84:87], v[64:79]
	ds_read_b64_tr_b16 v[178:179], v173 offset:10368
	ds_read_b64_tr_b16 v[180:181], v173 offset:12928
	v_add_f32_e32 v196, v196, v229
	v_cvt_pk_bf16_f32 v227, v228, v229
	v_exp_f32_e32 v230, v230
	v_exp_f32_e32 v231, v231
	s_waitcnt lgkmcnt(10)
	v_mfma_f32_32x32x16_bf16 v[48:63], v[182:185], v[84:87], v[48:63]
	ds_read_b64_tr_b16 v[182:183], v173 offset:10432
	ds_read_b64_tr_b16 v[184:185], v173 offset:12992
	v_add_f32_e32 v172, v172, v230
	v_add_f32_e32 v196, v196, v231
	v_cvt_pk_bf16_f32 v228, v230, v231
	v_exp_f32_e32 v232, v232
	s_waitcnt lgkmcnt(10)
	v_mfma_f32_32x32x16_bf16 v[32:47], v[2:5], v[84:87], v[32:47]
	ds_read_b64_tr_b16 v[2:3], v173 offset:15360
	ds_read_b64_tr_b16 v[4:5], v173 offset:17920
	v_exp_f32_e32 v233, v233
	v_add_f32_e32 v172, v172, v232
	v_add_f32_e32 v196, v196, v233
	v_cvt_pk_bf16_f32 v229, v232, v233
	s_waitcnt lgkmcnt(10)
	v_mfma_f32_32x32x16_bf16 v[16:31], v[6:9], v[84:87], v[16:31]
	ds_read_b64_tr_b16 v[6:7], v173 offset:15424
	ds_read_b64_tr_b16 v[8:9], v173 offset:17984
	s_cmp_lg_u32 s99, 0
	s_cbranch_scc0 .Lpc_skip5_i1
	s_and_b64 vcc, exec, s[12:13]
	s_cbranch_vccnz .Lpc_skip5_i1
	v_cndmask_b32_e64 v244, v166, v154, s[22:23]
	s_add_i32 m0, s98, s83
	s_nop 0
	global_load_lds_dwordx4 v244, s[36:37]
.Lpc_skip5_i1:
	s_waitcnt lgkmcnt(10)
	v_mfma_f32_32x32x16_bf16 v[64:79], v[10:13], v[226:229], v[64:79]
	ds_read_b64_tr_b16 v[10:11], v173 offset:15488
	ds_read_b64_tr_b16 v[12:13], v173 offset:18048
	v_exp_f32_e32 v234, v234
	v_exp_f32_e32 v235, v235
	v_add_f32_e32 v172, v172, v234
	v_add_f32_e32 v196, v196, v235
	v_cvt_pk_bf16_f32 v230, v234, v235
	s_waitcnt lgkmcnt(10)
	v_mfma_f32_32x32x16_bf16 v[48:63], v[174:177], v[226:229], v[48:63]
	ds_read_b64_tr_b16 v[174:175], v173 offset:15552
	ds_read_b64_tr_b16 v[176:177], v173 offset:18112
	v_exp_f32_e32 v236, v236
	v_exp_f32_e32 v237, v237
	v_add_f32_e32 v172, v172, v236
	v_add_f32_e32 v196, v196, v237
	v_cvt_pk_bf16_f32 v231, v236, v237
	s_waitcnt lgkmcnt(10)
	v_mfma_f32_32x32x16_bf16 v[32:47], v[178:181], v[226:229], v[32:47]
	v_exp_f32_e32 v238, v238
	v_exp_f32_e32 v239, v239
	v_add_f32_e32 v172, v172, v238
	v_add_f32_e32 v196, v196, v239
	v_cvt_pk_bf16_f32 v232, v238, v239
	s_waitcnt lgkmcnt(8)
	v_mfma_f32_32x32x16_bf16 v[16:31], v[182:185], v[226:229], v[16:31]
	v_exp_f32_e32 v240, v240
	v_exp_f32_e32 v241, v241
	v_add_f32_e32 v172, v172, v240
	v_add_f32_e32 v196, v196, v241
	v_cvt_pk_bf16_f32 v233, v240, v241
	s_waitcnt lgkmcnt(6)
	s_nop 0
	v_mfma_f32_32x32x16_bf16 v[64:79], v[2:5], v[230:233], v[64:79]
	s_waitcnt lgkmcnt(4)
	v_mfma_f32_32x32x16_bf16 v[48:63], v[6:9], v[230:233], v[48:63]
	s_waitcnt lgkmcnt(2)
	v_mfma_f32_32x32x16_bf16 v[32:47], v[10:13], v[230:233], v[32:47]
	s_cmp_lg_u32 s99, 0
	s_cbranch_scc0 .Lpc_skip4_i1
	s_andn2_b64 vcc, exec, s[68:69]
	s_cbranch_vccnz .Lpc_skip4_i1
	v_cndmask_b32_e64 v244, v168, v156, s[24:25]
	s_add_i32 m0, s98, s46
	s_nop 0
	global_load_lds_dwordx4 v244, s[36:37]

; template <bool DIFF, bool NOMAX>
; DI void unit(LAS unsigned char* lds, const Tensors& Tn, int b, int hd, int qb) {
;     ...
;     for (int j = jbeg; j < ntiles; ++j) {
;         const int sbn = (sb + NSTG - 1 >= NSTG) ? sb - 1 : sb + NSTG - 1;
;         if (j + NSTG - 1 < ntiles) ATT_ISSUE(j + NSTG - 1, sbn);
;         if (j >= jst && j < need) {
.LBB0_1488:
	s_cmp_gt_i32 s66, s41
	s_cbranch_scc0 .LBB0_1499
	s_add_i32 s26, s66, 2
	s_cmp_ge_i32 s26, s39
	s_cbranch_scc1 .LBB0_1496
	s_cmp_gt_i32 s31, 0
	s_cselect_b32 s26, -1, 2
	s_add_i32 s26, s26, s31
	s_mul_i32 s26, s26, 0xb400
	s_and_b64 vcc, exec, s[4:5]
	s_add_i32 s26, s26, 0
	s_cbranch_vccz .LBB0_1505
	s_andn2_b64 vcc, exec, s[18:19]
	s_cbranch_vccz .LBB0_1506

; template <bool DIFF, bool NOMAX>
; DI void unit(LAS unsigned char* lds, const Tensors& Tn, int b, int hd, int qb) {
;     ...
; #pragma unroll
;                 for (int ks = 0; ks < NKS; ++ks) {
;                     sc = mfma32(kf[ks % DK], qf[ks], sc);
;                     if (ks + DK < NKS) kf[ks % DK] = LDK(hf, ks + DK);
;                 }
; #pragma unroll
;                 for (int ks = 0; ks < NKS; ++ks) { SGB(0x8, 1); if (ks + DK < NKS) SGB(0x100, 1); }
;                 __builtin_amdgcn_sched_barrier(0);
; #pragma unroll
;                 for (int i = 0; i < DV; ++i) LDV(i, hf);
;                 if (DIFF && !offd) {
;                     const float qk = (float)(q0 + r - 64 * j - 4 * h - 32 * hf);
;                     float tq[4] = {qk, qk - 8.f, qk - 16.f, qk - 24.f};
; #pragma unroll
;                     for (int g = 0; g < 4; ++g) asm volatile("" : "+v"(tq[g]));
; #pragma unroll
;                     for (int e = 0; e < 16; ++e) sc[e] = __builtin_fmaf(-sl2, __builtin_fabsf(tq[e >> 2] - (float)(e & 3)), sc[e]);
;                 }
;                 float mx = sc[0];
;                 if (!NOMAX) {
; #pragma unroll
;                 for (int e = 1; e < 16; ++e) mx = __builtin_fmaxf(mx, sc[e]);
;                 { auto rr = __builtin_amdgcn_permlane32_swap(__builtin_bit_cast(unsigned, mx), __builtin_bit_cast(unsigned, mx), false, false);
;                   mx = __builtin_fmaxf(__builtin_bit_cast(float, rr[0]), __builtin_bit_cast(float, rr[1])); }
;                 }
;                 const bool first = (j == jst) && (hf == 0);
;                 if (!NOMAX && (first || __any(mx > 8.0f))) {
;                     const float mn = first ? mx : __builtin_fmaxf(mx, 0.f), al = first ? 1.0f : fast_exp2(-mn);
; #pragma unroll
;                     for (int dt = 0; dt < NDT; ++dt) o[dt] = o[dt] * al;
;                     lrow *= al; mrow += mn;
; #pragma unroll
;                     for (int e = 0; e < 16; ++e) sc[e] -= mn;
;                 }
;                 f32x2_t ps2 = {0.f, 0.f};
; #pragma unroll
;                 for (int e = 0; e < 16; e += 2) { sc[e] = fast_exp2(sc[e]); sc[e + 1] = fast_exp2(sc[e + 1]); ps2 += (f32x2_t){sc[e], sc[e + 1]}; }
;                 lrow += ps2.x + ps2.y;
;                 bf16x8 pb[2]; pb[0] = pack8(sc, 0); pb[1] = pack8(sc, 1);
; #pragma unroll
;                 for (int i = 0; i < NPV; ++i) {
.LBB0_1499:
	s_mul_i32 s26, s31, 0xb400
	s_add_i32 s26, s26, 0
	v_add3_u32 v202, s26, v156, v0
	s_add_i32 s99, s66, 2
	s_cmp_lt_i32 s99, s39
	s_cselect_b32 s99, 1, 0
	s_cmp_gt_i32 s31, 0
	s_cselect_b32 s98, -1, 2
	s_add_i32 s98, s98, s31
	s_mul_i32 s98, s98, 0xb400
	v_mov_b32_e32 v182, 0
	ds_read_b128 v[158:161], v202
	ds_read_b128 v[162:165], v202 offset:32
	ds_read_b128 v[166:169], v202 offset:64
	ds_read_b128 v[170:173], v202 offset:96
	ds_read_b128 v[174:177], v202 offset:128
	ds_read_b128 v[178:181], v202 offset:160
	v_add_u32_e32 v183, s26, v67
	v_add3_u32 v204, v183, v157, s1
	s_waitcnt lgkmcnt(5)
	v_mfma_f32_32x32x16_bf16 v[68:83], v[158:161], v[84:87], 0
	ds_read_b128 v[158:161], v202 offset:192
	s_waitcnt lgkmcnt(5)
	v_mfma_f32_32x32x16_bf16 v[68:83], v[162:165], v[88:91], v[68:83]
	ds_read_b128 v[162:165], v202 offset:224
	s_waitcnt lgkmcnt(5)
	v_mfma_f32_32x32x16_bf16 v[68:83], v[166:169], v[92:95], v[68:83]
	ds_read_b128 v[166:169], v202 offset:256
	s_waitcnt lgkmcnt(5)
	v_mfma_f32_32x32x16_bf16 v[68:83], v[170:173], v[96:99], v[68:83]
	ds_read_b128 v[170:173], v202 offset:288
	s_cmp_lg_u32 s99, 0
	s_cbranch_scc0 .Lpc_skip0_i2
	s_and_b64 vcc, exec, s[4:5]
	s_cbranch_vccnz .Lpc_skip0_i2
	v_cndmask_b32_e64 v244, v144, v132, s[6:7]
	s_add_i32 m0, s98, s29
	s_nop 0
	global_load_lds_dwordx4 v244, s[36:37]
.Lpc_skip0_i2:
	s_waitcnt lgkmcnt(5)
	v_mfma_f32_32x32x16_bf16 v[68:83], v[174:177], v[100:103], v[68:83]
	ds_read_b128 v[174:177], v202 offset:320
	s_waitcnt lgkmcnt(5)
	v_mfma_f32_32x32x16_bf16 v[68:83], v[178:181], v[104:107], v[68:83]
	ds_read_b128 v[178:181], v202 offset:352
	s_waitcnt lgkmcnt(5)
	v_mfma_f32_32x32x16_bf16 v[68:83], v[158:161], v[108:111], v[68:83]
	ds_read_b128 v[158:161], v202 offset:12800
	s_waitcnt lgkmcnt(5)
	v_mfma_f32_32x32x16_bf16 v[68:83], v[162:165], v[112:115], v[68:83]
	ds_read_b128 v[162:165], v202 offset:12832
	s_waitcnt lgkmcnt(5)
	v_mfma_f32_32x32x16_bf16 v[68:83], v[166:169], v[116:119], v[68:83]
	ds_read_b128 v[166:169], v202 offset:12864
	s_waitcnt lgkmcnt(5)
	v_mfma_f32_32x32x16_bf16 v[68:83], v[170:173], v[120:123], v[68:83]
	ds_read_b128 v[170:173], v202 offset:12896
	s_waitcnt lgkmcnt(5)
	v_mfma_f32_32x32x16_bf16 v[68:83], v[174:177], v[124:127], v[68:83]
	ds_read_b128 v[174:177], v202 offset:12928
	s_cmp_lg_u32 s99, 0
	s_cbranch_scc0 .Lpc_skip1_i2
	s_andn2_b64 vcc, exec, s[18:19]
	s_cbranch_vccnz .Lpc_skip1_i2
	v_cndmask_b32_e64 v244, v146, v134, s[8:9]
	s_add_i32 m0, s98, s47
	s_nop 0
	global_load_lds_dwordx4 v244, s[36:37]
.Lpc_skip1_i2:
	s_waitcnt lgkmcnt(5)
	v_mfma_f32_32x32x16_bf16 v[68:83], v[178:181], v[128:131], v[68:83]
	ds_read_b128 v[178:181], v202 offset:12960
	s_waitcnt lgkmcnt(5)
	v_mfma_f32_32x32x16_bf16 v[226:241], v[158:161], v[84:87], 0
	ds_read_b128 v[158:161], v202 offset:12992
	s_waitcnt lgkmcnt(5)
	v_mfma_f32_32x32x16_bf16 v[226:241], v[162:165], v[88:91], v[226:241]
	ds_read_b128 v[162:165], v202 offset:13024
	s_waitcnt lgkmcnt(5)
	v_mfma_f32_32x32x16_bf16 v[226:241], v[166:169], v[92:95], v[226:241]
	ds_read_b128 v[166:169], v202 offset:13056
	s_waitcnt lgkmcnt(5)
	v_mfma_f32_32x32x16_bf16 v[226:241], v[170:173], v[96:99], v[226:241]
	ds_read_b128 v[170:173], v202 offset:13088
	v_exp_f32_e32 v68, v68
	v_exp_f32_e32 v69, v69
	v_add_f32_e32 v66, v66, v68
	v_add_f32_e32 v182, v182, v69
	s_waitcnt lgkmcnt(5)
	v_mfma_f32_32x32x16_bf16 v[226:241], v[174:177], v[100:103], v[226:241]
	ds_read_b128 v[174:177], v202 offset:13120
	v_cvt_pk_bf16_f32 v68, v68, v69
	v_exp_f32_e32 v70, v70
	v_exp_f32_e32 v71, v71
	v_add_f32_e32 v66, v66, v70
	s_waitcnt lgkmcnt(5)
	v_mfma_f32_32x32x16_bf16 v[226:241], v[178:181], v[104:107], v[226:241]
	ds_read_b128 v[178:181], v202 offset:13152
	v_add_f32_e32 v182, v182, v71
	v_cvt_pk_bf16_f32 v69, v70, v71
	v_exp_f32_e32 v72, v72
	v_exp_f32_e32 v73, v73
	s_cmp_lg_u32 s99, 0
	s_cbranch_scc0 .Lpc_skip2_i2
	s_andn2_b64 vcc, exec, s[20:21]
	s_cbranch_vccnz .Lpc_skip2_i2
	v_cndmask_b32_e64 v244, v148, v136, s[10:11]
	s_add_i32 m0, s98, s50
	s_nop 0
	global_load_lds_dwordx4 v244, s[36:37]
.Lpc_skip2_i2:
	s_waitcnt lgkmcnt(5)
	v_mfma_f32_32x32x16_bf16 v[226:241], v[158:161], v[108:111], v[226:241]
	ds_read_b64_tr_b16 v[158:159], v204 offset:0
	ds_read_b64_tr_b16 v[160:161], v204 offset:2560
	v_add_f32_e32 v66, v66, v72
	v_add_f32_e32 v182, v182, v73
	v_cvt_pk_bf16_f32 v70, v72, v73
	v_exp_f32_e32 v74, v74
	v_exp_f32_e32 v75, v75
	s_waitcnt lgkmcnt(6)
	v_mfma_f32_32x32x16_bf16 v[226:241], v[162:165], v[112:115], v[226:241]
	ds_read_b64_tr_b16 v[162:163], v204 offset:64
	ds_read_b64_tr_b16 v[164:165], v204 offset:2624
	v_add_f32_e32 v66, v66, v74
	v_add_f32_e32 v182, v182, v75
	v_cvt_pk_bf16_f32 v71, v74, v75
	v_exp_f32_e32 v76, v76
	v_exp_f32_e32 v77, v77
	s_waitcnt lgkmcnt(7)
	v_mfma_f32_32x32x16_bf16 v[226:241], v[166:169], v[116:119], v[226:241]
	ds_read_b64_tr_b16 v[166:167], v204 offset:128
	ds_read_b64_tr_b16 v[168:169], v204 offset:2688
	v_add_f32_e32 v66, v66, v76
	v_add_f32_e32 v182, v182, v77
	v_cvt_pk_bf16_f32 v72, v76, v77
	v_exp_f32_e32 v78, v78
	v_exp_f32_e32 v79, v79
	s_waitcnt lgkmcnt(8)
	v_mfma_f32_32x32x16_bf16 v[226:241], v[170:173], v[120:123], v[226:241]
	ds_read_b64_tr_b16 v[170:171], v204 offset:192
	ds_read_b64_tr_b16 v[172:173], v204 offset:2752
	v_add_f32_e32 v66, v66, v78
	v_add_f32_e32 v182, v182, v79
	v_cvt_pk_bf16_f32 v73, v78, v79
	v_exp_f32_e32 v80, v80
	v_exp_f32_e32 v81, v81
	s_waitcnt lgkmcnt(9)
	v_mfma_f32_32x32x16_bf16 v[226:241], v[174:177], v[124:127], v[226:241]
	ds_read_b64_tr_b16 v[174:175], v204 offset:5120
	ds_read_b64_tr_b16 v[176:177], v204 offset:7680
	v_add_f32_e32 v66, v66, v80
	v_add_f32_e32 v182, v182, v81
	v_cvt_pk_bf16_f32 v74, v80, v81
	v_exp_f32_e32 v82, v82
	s_waitcnt lgkmcnt(10)
	v_mfma_f32_32x32x16_bf16 v[226:241], v[178:181], v[128:131], v[226:241]
	ds_read_b64_tr_b16 v[178:179], v204 offset:5184
	ds_read_b64_tr_b16 v[180:181], v204 offset:7744
	v_exp_f32_e32 v83, v83
	v_add_f32_e32 v66, v66, v82
	v_add_f32_e32 v182, v182, v83
	v_cvt_pk_bf16_f32 v75, v82, v83
	s_waitcnt lgkmcnt(10)
	v_mfma_f32_32x32x16_bf16 v[34:49], v[158:161], v[68:71], v[34:49]
	ds_read_b64_tr_b16 v[158:159], v204 offset:5248
	ds_read_b64_tr_b16 v[160:161], v204 offset:7808
	s_cmp_lg_u32 s99, 0
	s_cbranch_scc0 .Lpc_skip3_i2
	s_andn2_b64 vcc, exec, s[22:23]
	s_cbranch_vccnz .Lpc_skip3_i2
	v_cndmask_b32_e64 v244, v150, v138, s[12:13]
	s_add_i32 m0, s98, s51
	s_nop 0
	global_load_lds_dwordx4 v244, s[36:37]
; DI float fast_exp2(float x) { return __builtin_amdgcn_exp2f(x); }
; DI f32x16 mfma32(bf16x8 a, bf16x8 b, f32x16 c) { return __builtin_amdgcn_mfma_f32_32x32x16_bf16(a, b, c, 0, 0, 0); }
; #define LDV(i_, hf_) do { VTR(vlo[(i_) % DV], (16 * (2 * (hf_) + ((i_) & 1))) * VSTR + 64 * ((i_) >> 1)); VTR(vhi[(i_) % DV], (16 * (2 * (hf_) + ((i_) & 1)) + 8) * VSTR + 64 * ((i_) >> 1)); } while (0)
; #define VWAIT(n_, a_, b_) asm volatile("s_waitcnt lgkmcnt(%c2)" : "+v"(a_), "+v"(b_) : "i"(n_) : "memory")
; template <bool DIFF, bool NOMAX>
; DI void unit(LAS unsigned char* lds, const Tensors& Tn, int b, int hd, int qb) {
;     ...
;                 f32x2_t ps2 = {0.f, 0.f};
; #pragma unroll
;                 for (int e = 0; e < 16; e += 2) { sc[e] = fast_exp2(sc[e]); sc[e + 1] = fast_exp2(sc[e + 1]); ps2 += (f32x2_t){sc[e], sc[e + 1]}; }
;                 lrow += ps2.x + ps2.y;
;                 bf16x8 pb[2]; pb[0] = pack8(sc, 0); pb[1] = pack8(sc, 1);
; #pragma unroll
;                 for (int i = 0; i < NPV; ++i) {
;                     VWAIT(2 * ((NPV - 1 - i) < (DV - 1) ? (NPV - 1 - i) : (DV - 1)), vlo[i % DV], vhi[i % DV]);
;                     const bf16x8 vf = __builtin_shufflevector(vlo[i % DV], vhi[i % DV], 0, 1, 2, 3, 4, 5, 6, 7);
;                     o[i >> 1] = mfma32(vf, pb[i & 1], o[i >> 1]);
;                     if (i + DV < NPV) LDV(i + DV, hf);
;                 }
.Lpc_skip3_i2:
	s_waitcnt lgkmcnt(10)
	v_mfma_f32_32x32x16_bf16 v[50:65], v[162:165], v[68:71], v[50:65]
	ds_read_b64_tr_b16 v[162:163], v204 offset:5312
	ds_read_b64_tr_b16 v[164:165], v204 offset:7872
	s_waitcnt lgkmcnt(10)
	v_mfma_f32_32x32x16_bf16 v[18:33], v[166:169], v[68:71], v[18:33]
	ds_read_b64_tr_b16 v[166:167], v204 offset:10240
	ds_read_b64_tr_b16 v[168:169], v204 offset:12800
	v_exp_f32_e32 v226, v226
	v_exp_f32_e32 v227, v227
	v_add_f32_e32 v66, v66, v226
	v_add_f32_e32 v182, v182, v227
	s_waitcnt lgkmcnt(10)
	v_mfma_f32_32x32x16_bf16 v[2:17], v[170:173], v[68:71], v[2:17]
	ds_read_b64_tr_b16 v[170:171], v204 offset:10304
	ds_read_b64_tr_b16 v[172:173], v204 offset:12864
	v_cvt_pk_bf16_f32 v226, v226, v227
	v_exp_f32_e32 v228, v228
	v_exp_f32_e32 v229, v229
	v_add_f32_e32 v66, v66, v228
	s_waitcnt lgkmcnt(10)
	v_mfma_f32_32x32x16_bf16 v[34:49], v[174:177], v[72:75], v[34:49]
	ds_read_b64_tr_b16 v[174:175], v204 offset:10368
	ds_read_b64_tr_b16 v[176:177], v204 offset:12928
	v_add_f32_e32 v182, v182, v229
	v_cvt_pk_bf16_f32 v227, v228, v229
	v_exp_f32_e32 v230, v230
	v_exp_f32_e32 v231, v231
	s_waitcnt lgkmcnt(10)
	v_mfma_f32_32x32x16_bf16 v[50:65], v[178:181], v[72:75], v[50:65]
	ds_read_b64_tr_b16 v[178:179], v204 offset:10432
	ds_read_b64_tr_b16 v[180:181], v204 offset:12992
	v_add_f32_e32 v66, v66, v230
	v_add_f32_e32 v182, v182, v231
	v_cvt_pk_bf16_f32 v228, v230, v231
	v_exp_f32_e32 v232, v232
	s_waitcnt lgkmcnt(10)
	v_mfma_f32_32x32x16_bf16 v[18:33], v[158:161], v[72:75], v[18:33]
	ds_read_b64_tr_b16 v[158:159], v204 offset:15360
	ds_read_b64_tr_b16 v[160:161], v204 offset:17920
	v_exp_f32_e32 v233, v233
	v_add_f32_e32 v66, v66, v232
	v_add_f32_e32 v182, v182, v233
	v_cvt_pk_bf16_f32 v229, v232, v233
	s_waitcnt lgkmcnt(10)
	v_mfma_f32_32x32x16_bf16 v[2:17], v[162:165], v[72:75], v[2:17]
	ds_read_b64_tr_b16 v[162:163], v204 offset:15424
	ds_read_b64_tr_b16 v[164:165], v204 offset:17984
	s_cmp_lg_u32 s99, 0
	s_cbranch_scc0 .Lpc_skip5_i2
	s_andn2_b64 vcc, exec, s[64:65]
	s_cbranch_vccnz .Lpc_skip5_i2
	v_cndmask_b32_e64 v244, v154, v142, s[16:17]
	s_add_i32 m0, s98, s57
	s_nop 0
	global_load_lds_dwordx4 v244, s[36:37]
.Lpc_skip5_i2:
	s_waitcnt lgkmcnt(10)
	v_mfma_f32_32x32x16_bf16 v[34:49], v[166:169], v[226:229], v[34:49]
	ds_read_b64_tr_b16 v[166:167], v204 offset:15488
	ds_read_b64_tr_b16 v[168:169], v204 offset:18048
	v_exp_f32_e32 v234, v234
	v_exp_f32_e32 v235, v235
	v_add_f32_e32 v66, v66, v234
	v_add_f32_e32 v182, v182, v235
	v_cvt_pk_bf16_f32 v230, v234, v235
	s_waitcnt lgkmcnt(10)
	v_mfma_f32_32x32x16_bf16 v[50:65], v[170:173], v[226:229], v[50:65]
	ds_read_b64_tr_b16 v[170:171], v204 offset:15552
	ds_read_b64_tr_b16 v[172:173], v204 offset:18112
	v_exp_f32_e32 v236, v236
	v_exp_f32_e32 v237, v237
	v_add_f32_e32 v66, v66, v236
	v_add_f32_e32 v182, v182, v237
	v_cvt_pk_bf16_f32 v231, v236, v237
	s_waitcnt lgkmcnt(10)
	v_mfma_f32_32x32x16_bf16 v[18:33], v[174:177], v[226:229], v[18:33]
	v_exp_f32_e32 v238, v238
	v_exp_f32_e32 v239, v239
	v_add_f32_e32 v66, v66, v238
	v_add_f32_e32 v182, v182, v239
	v_cvt_pk_bf16_f32 v232, v238, v239
	s_waitcnt lgkmcnt(8)
	v_mfma_f32_32x32x16_bf16 v[2:17], v[178:181], v[226:229], v[2:17]
	v_exp_f32_e32 v240, v240
	v_exp_f32_e32 v241, v241
	v_add_f32_e32 v66, v66, v240
	v_add_f32_e32 v182, v182, v241
	v_cvt_pk_bf16_f32 v233, v240, v241
	s_waitcnt lgkmcnt(6)
	s_nop 0
	v_mfma_f32_32x32x16_bf16 v[34:49], v[158:161], v[230:233], v[34:49]
	s_waitcnt lgkmcnt(4)
	v_mfma_f32_32x32x16_bf16 v[50:65], v[162:165], v[230:233], v[50:65]
	s_waitcnt lgkmcnt(2)
	v_mfma_f32_32x32x16_bf16 v[18:33], v[166:169], v[230:233], v[18:33]
	s_cmp_lg_u32 s99, 0
	s_cbranch_scc0 .Lpc_skip4_i2
	s_andn2_b64 vcc, exec, s[24:25]
	s_cbranch_vccnz .Lpc_skip4_i2
	v_cndmask_b32_e64 v244, v152, v140, s[14:15]
	s_add_i32 m0, s98, s56
	s_nop 0
	global_load_lds_dwordx4 v244, s[36:37]
.Lpc_skip4_i2:
	s_waitcnt lgkmcnt(0)
	v_mfma_f32_32x32x16_bf16 v[2:17], v[170:173], v[230:233], v[2:17]
	v_add_f32_e32 v66, v66, v182
	s_cmp_ge_i32 s66, s46
	s_mov_b64 s[26:27], -1
	s_cbranch_scc0 .LBB0_1498
